# S5-Y tile map: the two vblocks of a CU take the same (g,mt) rows with different t-blocks so they share A rows in L1/L2
# baseline (speedup 1.0000x reference)
; #define VBID ((int)(blockIdx.x * 2 + (otid() >> 8)))
; #define LAS __attribute__((address_space(3)))
; template <class FA, class FB, class FL, class FS>
; DI void gemm_tile(char* lds, int ksteps, int rot, FA fa, FB fb, FL fl, FS fs) {
;     ...
; #pragma unroll
;   for (int i = 0; i < 4; ++i) {
;     const int id = tid + i * 256, r = id >> 3, c = (id & 7) ^ (r & 7);
;     __builtin_amdgcn_global_load_lds((const unsigned*)fa(r, rot * 8 + c), (LAS unsigned*)(l3 + id * 16), 16, 0, 0);
;     __builtin_amdgcn_global_load_lds((const unsigned*)fb(r, rot * 8 + c), (LAS unsigned*)(l3 + 16384 + id * 16), 16, 0, 0);
;   }
;   asm volatile("s_waitcnt vmcnt(0)" ::: "memory");
;   __syncthreads();
; DI void phase_s5_y(const Params& p, char* lds) {
;     ...
;   for (int k_ = 0; k_ * VGRID < (nt); ++k_) {
;     int L = k_ * VGRID + VBID; const bool active_ = L < (nt); if (!active_) L = (nt) - 1;
;     const int j = 3 - (L >> 10), rem = L & 1023, g = rem >> 4, mt = rem & 15;
;     const bf16_t* Ug = ugm + (size_t)g * MP * 16 + (size_t)mt * 128 * 512;
;     const bf16_t* Hg = H + ((size_t)g * 2048 + mt * 128) * 128;
;     gemm_tile(lds, 2 + 2 * (j + 1), 0,
;       [&](int r, int kc) { return kc < 16 ? Hg + (size_t)r * 128 + kc * 8 : Ug + (size_t)r * 512 + (kc - 16) * 8; },
;       [&](int n, int kc) {
;         const int nn = j * 128 + n;
;         if (kc < 16) return MC + ((size_t)g * 512 + nn) * 128 + kc * 8;
;         const int t = nn >> 4, co = nn & 15, kk = (kc - 16) * 8, s = kk >> 4, ci0 = kk & 15;
;         if (s > t) return zblk;
;         return KT + ((size_t)(g * 16 + co) * 32 + (t - s)) * 16 + ci0;
;       },
.LBB0_625:
	v_mov_b32_e32 v0, v182
	v_readlane_b32 s1, v251, 7
	v_ashrrev_i32_e32 v0, 8, v0
	s_add_i32 s0, s0, s1
	v_add_u32_e32 v0, s0, v0
	v_min_i32_e32 v0, 0xfff, v0
	v_lshrrev_b32_e32 v70, 10, v0
	v_xor_b32_e32 v71, v70, v0
	v_and_b32_e32 v71, 1, v71
	v_lshlrev_b32_e32 v71, 10, v71
	v_and_b32_e32 v70, 1, v70
	v_or_b32_e32 v70, v70, v71
	v_and_b32_e32 v71, 0x1fe, v0
	v_or_b32_e32 v70, v70, v71
	v_lshrrev_b32_e32 v71, 2, v0
	v_and_b32_e32 v71, 0x200, v71
	v_or_b32_e32 v70, v70, v71
	v_lshlrev_b32_e32 v71, 2, v0
	v_and_b32_e32 v71, 0x800, v71
	v_or_b32_e32 v0, v70, v71
	v_bfe_u32 v70, v0, 4, 6
	v_and_b32_e32 v71, 15, v0
	v_lshlrev_b32_e32 v68, 19, v70
	v_mov_b32_e32 v26, v182
	v_ashrrev_i32_e32 v154, 10, v0
	v_lshl_add_u64 v[0:1], s[8:9], 0, v[68:69]
	v_lshlrev_b32_e32 v68, 15, v71
	v_lshl_add_u64 v[6:7], v[0:1], 0, v[68:69]
	v_bfe_u32 v24, v26, 3, 5
	v_xor_b32_e32 v0, v24, v26
	v_lshlrev_b32_sdwa v82, v103, v26 dst_sel:DWORD dst_unused:UNUSED_PAD src0_sel:DWORD src1_sel:BYTE_0
	v_lshlrev_b32_e32 v68, 8, v24
	v_lshlrev_b32_e32 v0, 4, v0
	v_add_u32_e32 v56, v102, v82
	v_sub_u32_e32 v91, 3, v154
	v_lshl_add_u64 v[8:9], v[6:7], 0, v[68:69]
	v_and_b32_e32 v68, 0x70, v0
	v_readfirstlane_b32 s0, v56
	v_lshl_add_u64 v[0:1], v[8:9], 0, v[68:69]
	s_mov_b32 m0, s0
	v_lshlrev_b32_e32 v81, 7, v91
	global_load_lds_dwordx4 v[0:1], off
	v_or_b32_e32 v0, v81, v24
	v_mov_b32_e32 v1, v69
	v_lshlrev_b32_e32 v2, 17, v70
	v_mov_b32_e32 v3, v69
	v_lshl_add_u64 v[10:11], s[10:11], 0, v[2:3]
	v_lshlrev_b64 v[2:3], 8, v[0:1]
	v_add_u32_e32 v1, 0x4000, v56
	v_lshl_add_u64 v[22:23], v[10:11], 0, v[2:3]
	v_readfirstlane_b32 s0, v1
	v_or_b32_sdwa v1, v26, s33 dst_sel:DWORD dst_unused:UNUSED_PAD src0_sel:BYTE_0 src1_sel:DWORD
	v_lshl_add_u64 v[2:3], v[22:23], 0, v[68:69]
	s_mov_b32 m0, s0
	v_lshrrev_b32_e32 v155, 3, v1
	global_load_lds_dwordx4 v[2:3], off
	v_xor_b32_e32 v2, v155, v26
	v_lshlrev_b32_e32 v83, 4, v1
	v_lshlrev_b32_e32 v68, 8, v155
	v_lshlrev_b32_e32 v2, 4, v2
	v_add_u32_e32 v1, v102, v83
	v_lshl_add_u64 v[60:61], v[6:7], 0, v[68:69]
	v_and_b32_e32 v68, 0x70, v2
	v_readfirstlane_b32 s0, v1
	v_lshl_add_u64 v[2:3], v[60:61], 0, v[68:69]
	s_mov_b32 m0, s0
	v_lshrrev_b32_e32 v80, 4, v26
	global_load_lds_dwordx4 v[2:3], off
	v_or_b32_e32 v2, v81, v155
	v_mov_b32_e32 v3, v69
	v_lshlrev_b64 v[4:5], 8, v[2:3]
	v_add_u32_e32 v3, 0x4000, v1
	v_lshl_add_u64 v[62:63], v[10:11], 0, v[4:5]
	v_readfirstlane_b32 s0, v3
	v_or_b32_sdwa v3, v26, s34 dst_sel:DWORD dst_unused:UNUSED_PAD src0_sel:BYTE_0 src1_sel:DWORD
	v_lshl_add_u64 v[4:5], v[62:63], 0, v[68:69]
	s_mov_b32 m0, s0
	v_lshrrev_b32_e32 v156, 3, v3
	global_load_lds_dwordx4 v[4:5], off
	v_xor_b32_e32 v4, v156, v26
	v_lshlrev_b32_e32 v84, 4, v3
	v_lshlrev_b32_e32 v68, 8, v156
	v_lshlrev_b32_e32 v4, 4, v4
	v_add_u32_e32 v3, v102, v84
	v_lshl_add_u64 v[64:65], v[6:7], 0, v[68:69]
	v_and_b32_e32 v68, 0x70, v4
	v_readfirstlane_b32 s0, v3
	v_lshl_add_u64 v[4:5], v[64:65], 0, v[68:69]
	s_mov_b32 m0, s0
	v_and_b32_e32 v25, 7, v26
	global_load_lds_dwordx4 v[4:5], off
	v_or_b32_e32 v4, v81, v156
	v_mov_b32_e32 v5, v69
	v_lshlrev_b64 v[12:13], 8, v[4:5]
	v_add_u32_e32 v5, 0x4000, v3
	v_lshl_add_u64 v[76:77], v[10:11], 0, v[12:13]
	v_readfirstlane_b32 s0, v5
	v_or_b32_sdwa v5, v26, s35 dst_sel:DWORD dst_unused:UNUSED_PAD src0_sel:BYTE_0 src1_sel:DWORD
	v_lshl_add_u64 v[12:13], v[76:77], 0, v[68:69]
	s_mov_b32 m0, s0
	v_lshrrev_b32_e32 v157, 3, v5
	global_load_lds_dwordx4 v[12:13], off
	v_xor_b32_e32 v12, v157, v26
	v_lshlrev_b32_e32 v68, 8, v157
	v_lshlrev_b32_e32 v85, 4, v5
	v_lshl_add_u64 v[100:101], v[6:7], 0, v[68:69]
	v_lshlrev_b32_e32 v6, 4, v12
	v_add_u32_e32 v5, v102, v85
	v_and_b32_e32 v68, 0x70, v6
	v_readfirstlane_b32 s0, v5
	v_lshl_add_u64 v[6:7], v[100:101], 0, v[68:69]
	s_mov_b32 m0, s0
	v_and_b32_e32 v79, 15, v26
	global_load_lds_dwordx4 v[6:7], off
	v_or_b32_e32 v6, v81, v157
	v_mov_b32_e32 v7, v69
	v_lshlrev_b64 v[12:13], 8, v[6:7]
	v_add_u32_e32 v7, 0x4000, v5
	v_lshl_add_u64 v[148:149], v[10:11], 0, v[12:13]
	v_readfirstlane_b32 s0, v7
	v_lshl_add_u64 v[10:11], v[148:149], 0, v[68:69]
	s_mov_b32 m0, s0
	v_lshlrev_b32_e32 v68, 21, v70
	global_load_lds_dwordx4 v[10:11], off
	v_lshl_add_u64 v[10:11], s[6:7], 0, v[68:69]
	v_lshlrev_b32_e32 v68, 17, v71
	v_bfe_u32 v7, v26, 4, 2
	v_lshl_add_u64 v[152:153], v[10:11], 0, v[68:69]
	v_bitop3_b32 v10, v80, v25, 3 bitop3:0x6c
	v_bitop3_b32 v7, v7, v25, 4 bitop3:0x36
	v_bfe_u32 v78, v26, 6, 1
	v_bfe_u32 v86, v26, 7, 1
	v_lshlrev_b32_e32 v87, 4, v10
	v_lshlrev_b32_e32 v14, 7, v79
	v_lshlrev_b32_e32 v90, 4, v7
	v_lshlrev_b32_e32 v7, 7, v26
	v_lshl_or_b32 v88, v78, 13, v14
	v_add_u32_e32 v15, v102, v87
	v_lshl_or_b32 v89, v86, 13, v14
	v_lshlrev_b32_e32 v68, 10, v24
	v_and_b32_e32 v7, 0x3c00, v7
	v_bitop3_b32 v158, v24, 7, v26 bitop3:0x48
	v_add_u32_e32 v27, v15, v88
	v_add_u32_e32 v57, v15, v89
	v_lshl_add_u64 v[24:25], v[152:153], 0, v[68:69]
	v_lshl_or_b32 v68, v70, 14, v7
	s_waitcnt vmcnt(0)
	s_waitcnt vmcnt(0) lgkmcnt(0)
	s_barrier
; #define MFMA16(a, b, c) __builtin_amdgcn_mfma_f32_16x16x32_bf16((a), (b), (c), 0, 0, 0)
; #define LAS __attribute__((address_space(3)))
; template <class FA, class FB, class FL, class FS>
; DI void gemm_tile(char* lds, int ksteps, int rot, FA fa, FB fb, FL fl, FS fs) {
;     ...
;   for (int ks = 0; ks < ksteps; ++ks) {
;     const int cur = ks & 1;
;     if (ks + 1 < ksteps) {
;       int kn = ks + 1 + rot; if (kn >= ksteps) kn -= ksteps;
;       LAS char* dst = l3 + (cur ^ 1) * 32768;
; #pragma unroll
;       for (int i = 0; i < 4; ++i) {
;         const int id = tid + i * 256, r = id >> 3, c = (id & 7) ^ (r & 7);
;         __builtin_amdgcn_global_load_lds((const unsigned*)fa(r, kn * 8 + c), (LAS unsigned*)(dst + id * 16), 16, 0, 0);
;         __builtin_amdgcn_global_load_lds((const unsigned*)fb(r, kn * 8 + c), (LAS unsigned*)(dst + 16384 + id * 16), 16, 0, 0);
;       }
;     }
;     const char* A = lds + cur * 32768;
;     const char* B = A + 16384;
; #pragma unroll
;     for (int kk = 0; kk < 2; ++kk) {
;       bf16x8 af[4], bq[4];
; #pragma unroll
;       for (int m = 0; m < 4; ++m) af[m] = ldfrag(A, 128, wr * 64 + m * 16 + fr, kk * 4 + fq);
; #pragma unroll
;       for (int n = 0; n < 4; ++n) bq[n] = ldfrag(B, 128, wc * 64 + n * 16 + fr, kk * 4 + fq);
; #pragma unroll
;       for (int m = 0; m < 4; ++m)
; #pragma unroll
;         for (int n = 0; n < 4; ++n) acc[m][n] = MFMA16(bq[n], af[m], acc[m][n]);
	ds_read_b128 v[10:13], v27 offset:16384
	ds_read_b128 v[14:17], v57
	ds_read_b128 v[18:21], v27 offset:18432
	v_bitop3_b32 v159, v155, 7, v26 bitop3:0x48
	ds_read_b128 v[28:31], v57 offset:2048
	ds_read_b128 v[32:35], v27 offset:20480
	v_bitop3_b32 v160, v156, 7, v26 bitop3:0x48
	v_bitop3_b32 v161, v157, 7, v26 bitop3:0x48
	ds_read_b128 v[40:43], v27 offset:22528
	v_lshl_add_u64 v[26:27], s[12:13], 0, v[68:69]
	v_lshlrev_b32_e32 v68, 4, v158
	v_add_u32_e32 v7, 0x8000, v56
	v_lshl_add_u64 v[8:9], v[8:9], 0, v[68:69]
	v_readfirstlane_b32 s0, v7
	v_lshl_add_u64 v[8:9], v[8:9], 0, s[16:17]
	s_mov_b32 m0, s0
	v_add_u32_e32 v7, 0xc000, v56
	global_load_lds_dwordx4 v[8:9], off
	v_lshl_add_u64 v[8:9], v[22:23], 0, v[68:69]
	v_readfirstlane_b32 s0, v7
	v_add_u32_e32 v7, 0x8000, v1
	v_lshl_add_u64 v[8:9], v[8:9], 0, s[16:17]
	s_mov_b32 m0, s0
	v_readfirstlane_b32 s0, v7
	v_add_u32_e32 v1, 0xc000, v1
	global_load_lds_dwordx4 v[8:9], off
	s_mov_b32 m0, s0
	v_readfirstlane_b32 s0, v1
	v_add_u32_e32 v1, v102, v90
	v_lshlrev_b32_e32 v68, 4, v159
	v_add_u32_e32 v7, v1, v88
	ds_read_b128 v[52:55], v57 offset:4096
	ds_read_b128 v[124:127], v7 offset:16384
	ds_read_b128 v[56:59], v57 offset:6144
	v_lshl_add_u64 v[8:9], v[60:61], 0, v[68:69]
	v_lshl_add_u64 v[8:9], v[8:9], 0, s[16:17]
	global_load_lds_dwordx4 v[8:9], off
	v_lshl_add_u64 v[8:9], v[62:63], 0, v[68:69]
	v_lshl_add_u64 v[22:23], v[8:9], 0, s[16:17]
	s_mov_b32 m0, s0
	v_add_u32_e32 v1, v1, v89
	global_load_lds_dwordx4 v[22:23], off
	s_waitcnt lgkmcnt(0)
	v_mfma_f32_16x16x32_bf16 v[44:47], v[18:21], v[14:17], 0
	v_lshlrev_b32_e32 v68, 4, v160
	v_add_u32_e32 v22, 0x8000, v3
	v_add_u32_e32 v3, 0xc000, v3
	v_mfma_f32_16x16x32_bf16 v[48:51], v[32:35], v[14:17], 0
	v_readfirstlane_b32 s0, v22
	s_mov_b32 m0, s0
	v_readfirstlane_b32 s0, v3
	v_mfma_f32_16x16x32_bf16 v[92:95], v[18:21], v[28:31], 0
	v_add_u32_e32 v3, 0x8000, v5
	v_lshl_add_u32 v91, v91, 1, 4
	s_mov_b32 s37, -9
	v_mfma_f32_16x16x32_bf16 v[96:99], v[32:35], v[28:31], 0
	s_mov_b32 s38, 0
	s_mov_b32 s39, 0x8000
	v_mfma_f32_16x16x32_bf16 v[108:111], v[18:21], v[52:55], 0
	v_mfma_f32_16x16x32_bf16 v[112:115], v[32:35], v[52:55], 0
	v_mfma_f32_16x16x32_bf16 v[120:123], v[18:21], v[56:59], 0
	ds_read_b128 v[18:21], v1
	ds_read_b128 v[132:135], v7 offset:18432
	v_mfma_f32_16x16x32_bf16 v[128:131], v[32:35], v[56:59], 0
	ds_read_b128 v[32:35], v1 offset:2048
	ds_read_b128 v[140:143], v7 offset:20480
	ds_read_b128 v[144:147], v7 offset:22528
	v_mfma_f32_16x16x32_bf16 v[36:39], v[10:13], v[14:17], 0
	v_mfma_f32_16x16x32_bf16 v[72:75], v[10:13], v[28:31], 0
	v_mfma_f32_16x16x32_bf16 v[104:107], v[10:13], v[52:55], 0
	v_mfma_f32_16x16x32_bf16 v[8:11], v[10:13], v[56:59], 0
	v_lshl_add_u64 v[12:13], v[64:65], 0, v[68:69]
	v_lshl_add_u64 v[12:13], v[12:13], 0, s[16:17]
	global_load_lds_dwordx4 v[12:13], off
	v_lshl_add_u64 v[12:13], v[76:77], 0, v[68:69]
	v_mfma_f32_16x16x32_bf16 v[14:17], v[40:43], v[14:17], 0
	v_lshl_add_u64 v[12:13], v[12:13], 0, s[16:17]
	s_mov_b32 m0, s0
	v_lshlrev_b32_e32 v68, 4, v161
	global_load_lds_dwordx4 v[12:13], off
	v_lshl_add_u64 v[12:13], v[100:101], 0, v[68:69]
	v_readfirstlane_b32 s0, v3
	v_lshl_add_u64 v[12:13], v[12:13], 0, s[16:17]
	s_mov_b32 m0, s0
	v_add_u32_e32 v3, 0xc000, v5
	global_load_lds_dwordx4 v[12:13], off
	v_lshl_add_u64 v[12:13], v[148:149], 0, v[68:69]
	v_readfirstlane_b32 s0, v3
	v_mfma_f32_16x16x32_bf16 v[116:119], v[40:43], v[52:55], 0
	s_mov_b32 m0, s0
	ds_read_b128 v[148:151], v1 offset:6144
	v_lshlrev_b32_e32 v76, 10, v157
	s_waitcnt lgkmcnt(0)
	v_mfma_f32_16x16x32_bf16 v[52:55], v[144:147], v[18:21], v[14:17]
	v_mov_b32_e32 v77, v69
	v_lshlrev_b32_e32 v68, 1, v154
	v_lshl_add_u64 v[76:77], v[152:153], 0, v[76:77]
	v_lshl_add_u64 v[16:17], v[12:13], 0, s[16:17]
	global_load_lds_dwordx4 v[16:17], off
	ds_read_b128 v[12:15], v1 offset:4096
	v_mfma_f32_16x16x32_bf16 v[28:31], v[40:43], v[28:31], 0
	s_waitcnt vmcnt(0)
	v_sub_u32_e32 v100, 0, v68
	s_mov_b64 s[0:1], 0
	v_mfma_f32_16x16x32_bf16 v[136:139], v[40:43], v[56:59], 0
	s_waitcnt lgkmcnt(0)
	s_barrier
	v_mfma_f32_16x16x32_bf16 v[64:67], v[124:127], v[18:21], v[36:39]
	v_mfma_f32_16x16x32_bf16 v[60:63], v[132:135], v[18:21], v[44:47]
	v_mfma_f32_16x16x32_bf16 v[56:59], v[140:143], v[18:21], v[48:51]
	v_mfma_f32_16x16x32_bf16 v[48:51], v[124:127], v[32:35], v[72:75]
	v_mfma_f32_16x16x32_bf16 v[44:47], v[132:135], v[32:35], v[92:95]
	s_nop 1
	v_lshlrev_b32_e32 v72, 10, v155
	v_mov_b32_e32 v73, v69
	v_lshlrev_b32_e32 v74, 10, v156
	v_mfma_f32_16x16x32_bf16 v[40:43], v[140:143], v[32:35], v[96:99]
	v_lshrrev_b32_e32 v92, 4, v0
	v_lshrrev_b32_e32 v93, 4, v2
	v_lshrrev_b32_e32 v94, 4, v4
	v_mfma_f32_16x16x32_bf16 v[36:39], v[144:147], v[32:35], v[28:31]
	v_lshrrev_b32_e32 v95, 4, v6
	v_mov_b32_e32 v75, v69
	v_lshl_add_u64 v[72:73], v[152:153], 0, v[72:73]
	v_mfma_f32_16x16x32_bf16 v[32:35], v[124:127], v[12:15], v[104:107]
	v_lshl_add_u64 v[74:75], v[152:153], 0, v[74:75]
	v_lshlrev_b32_e32 v96, 3, v158
	v_lshlrev_b32_e32 v97, 3, v159
	v_mfma_f32_16x16x32_bf16 v[28:31], v[132:135], v[12:15], v[108:111]
	v_lshlrev_b32_e32 v98, 3, v160
	v_lshlrev_b32_e32 v99, 3, v161
	v_mfma_f32_16x16x32_bf16 v[20:23], v[140:143], v[12:15], v[112:115]
	v_mfma_f32_16x16x32_bf16 v[16:19], v[144:147], v[12:15], v[116:119]
	v_mfma_f32_16x16x32_bf16 v[12:15], v[124:127], v[148:151], v[8:11]
	v_mfma_f32_16x16x32_bf16 v[8:11], v[132:135], v[148:151], v[120:123]
	v_mfma_f32_16x16x32_bf16 v[4:7], v[140:143], v[148:151], v[128:131]
	v_mfma_f32_16x16x32_bf16 v[0:3], v[144:147], v[148:151], v[136:139]
	s_branch .LBB0_627
